# v22 + nt hint on the write-once conv-state output stores (global_store_dword) in the ssd sample-step loops
# speedup vs baseline: 1.0015x; 1.0015x over previous
; __device__ __forceinline__ float siluf_(float x) { return x * frcp_(1.0f + __expf(-x)); }
; __device__ __forceinline__ float softplusf_(float x) { return x > 20.f ? x : log1pf(__expf(x)); }
; __device__ __forceinline__ void ssd_sample_step(const bf16* proj, const float* conv_w, const float* conv_b, const float* dt_bias, const float* a_log, const float* d_skip, const float* ssm_norm, ...
;     ...
;         const float a = cbb + cw0 * r0 + cw1 * r1 + cw2 * r2 + cw3 * cur;
;         const float v = siluf_(a);
;         if (tid < 256) sx[tid] = v; else if (tid < 384) sB[tid - 256] = v; else sC[tid - 384] = v;
;         float* co = conv_out + (size_t)b * 3 * 4096; co[chx] = r1; co[4096 + chx] = r2; co[8192 + chx] = cur;
;         if (tid < 4) { const float dv = softplusf_(dtr + dtbv); sdt[tid] = dv; sdec[tid] = __expf(dv * (-__expf(alg))); } }
.LBB0_455:
	s_or_saveexec_b64 s[6:7], s[6:7]
	v_lshl_add_u32 v10, v8, 2, 0
	s_xor_b64 exec, exec, s[6:7]
	ds_write_b32 v10, v75 offset:2048
	s_or_b64 exec, exec, s[6:7]
	s_add_u32 s6, s22, s12
	s_addc_u32 s7, s23, s13
	v_lshl_add_u64 v[68:69], v[68:69], 2, s[6:7]
	v_add_co_u32_e32 v76, vcc, 0x4000, v68
	global_store_dword v[68:69], v70, off nt
	s_nop 0
	v_addc_co_u32_e32 v77, vcc, 0, v69, vcc
	v_add_co_u32_e32 v68, vcc, 0x8000, v68
	global_store_dword v[76:77], v71, off nt
	s_nop 0
	v_addc_co_u32_e32 v69, vcc, 0, v69, vcc
	global_store_dword v[68:69], v74, off nt
	s_and_saveexec_b64 s[6:7], s[8:9]
	s_cbranch_execz .LBB0_461
	v_add_f32_e32 v68, v73, v72
	v_cmp_nlt_f32_e32 vcc, s54, v68
	s_and_saveexec_b64 s[8:9], vcc
	s_cbranch_execz .LBB0_460
	v_mul_f32_e32 v68, 0x3fb8aa3b, v68
	v_exp_f32_e32 v81, v68
	s_mov_b32 s12, 0x3f2aaaab
	v_add_f32_e32 v70, 1.0, v81
	v_frexp_mant_f32_e32 v72, v70
	v_cvt_f64_f32_e32 v[68:69], v70
	v_frexp_exp_i32_f64_e32 v68, v[68:69]
	v_cmp_gt_f32_e32 vcc, s12, v72
	v_add_f32_e32 v71, -1.0, v70
	v_sub_f32_e32 v73, v71, v70
	v_subbrev_co_u32_e32 v76, vcc, 0, v68, vcc
	v_sub_u32_e32 v68, 0, v76
	v_sub_f32_e32 v71, v81, v71
	v_add_f32_e32 v73, 1.0, v73
	v_ldexp_f32 v69, v70, v68
	v_add_f32_e32 v71, v71, v73
	v_add_f32_e32 v70, -1.0, v69
	v_add_f32_e32 v72, 1.0, v69
	v_ldexp_f32 v68, v71, v68
	v_add_f32_e32 v71, 1.0, v70
	v_add_f32_e32 v73, -1.0, v72
	v_sub_f32_e32 v71, v69, v71
	v_sub_f32_e32 v69, v69, v73
	v_add_f32_e32 v71, v68, v71
	v_add_f32_e32 v68, v68, v69
	v_add_f32_e32 v77, v72, v68
	v_rcp_f32_e32 v79, v77
	v_sub_f32_e32 v69, v77, v72
	v_sub_f32_e32 v78, v68, v69
	v_add_f32_e32 v69, v70, v71
	v_mul_f32_e32 v83, v69, v79
	v_sub_f32_e32 v68, v69, v70
	v_mul_f32_e32 v70, v77, v83
	v_fma_f32 v72, v83, v77, -v70
	v_fmac_f32_e32 v72, v83, v78
	v_sub_f32_e32 v82, v71, v68
	v_add_f32_e32 v68, v70, v72
	v_sub_f32_e32 v71, v69, v68
	v_pk_add_f32 v[74:75], v[68:69], v[70:71] neg_lo:[0,1] neg_hi:[0,1]
	v_mov_b32_e32 v73, v68
	v_pk_add_f32 v[68:69], v[74:75], v[72:73] neg_lo:[0,1] neg_hi:[0,1]
	s_mov_b32 s12, 0x3f317218
	v_add_f32_e32 v69, v82, v69
	v_add_f32_e32 v68, v68, v69
	v_add_f32_e32 v69, v71, v68
	v_mul_f32_e32 v82, v79, v69
	v_mul_f32_e32 v70, v77, v82
	v_fma_f32 v72, v82, v77, -v70
	v_fmac_f32_e32 v72, v82, v78
	v_sub_f32_e32 v71, v71, v69
	v_add_f32_e32 v77, v68, v71
	v_add_f32_e32 v68, v70, v72
	v_sub_f32_e32 v71, v69, v68
	v_pk_add_f32 v[74:75], v[68:69], v[70:71] neg_lo:[0,1] neg_hi:[0,1]
	v_mov_b32_e32 v73, v68
	v_pk_add_f32 v[68:69], v[74:75], v[72:73] neg_lo:[0,1] neg_hi:[0,1]
	v_cmp_neq_f32_e32 vcc, s81, v81
	v_add_f32_e32 v69, v77, v69
	v_add_f32_e32 v68, v68, v69
	v_add_f32_e32 v69, v83, v82
	v_add_f32_e32 v68, v71, v68
	v_sub_f32_e32 v70, v69, v83
	v_mul_f32_e32 v68, v79, v68
	v_sub_f32_e32 v70, v82, v70
	v_add_f32_e32 v70, v70, v68
	v_add_f32_e32 v72, v69, v70
	v_mul_f32_e32 v73, v72, v72
	v_fmamk_f32 v68, v73, 0x3e9b6dac, v178
	v_fmaak_f32 v149, v73, v68, 0x3f2aaada
	v_cvt_f32_i32_e32 v68, v76
	v_sub_f32_e32 v69, v72, v69
	v_sub_f32_e32 v69, v70, v69
	v_ldexp_f32 v74, v69, 1
	v_mul_f32_e32 v69, v72, v73
	v_ldexp_f32 v71, v72, 1
	v_pk_mul_f32 v[72:73], v[68:69], v[148:149]
	s_nop 0
	v_fma_f32 v70, v68, s12, -v72
	v_fmac_f32_e32 v70, 0xb102e308, v68
	v_pk_add_f32 v[68:69], v[72:73], v[70:71]
	s_mov_b32 s12, 0x33800000
	v_sub_f32_e32 v71, v69, v71
	v_sub_f32_e32 v71, v73, v71
	v_add_f32_e32 v75, v74, v71
	v_mov_b32_e32 v74, v72
	v_pk_add_f32 v[72:73], v[68:69], v[72:73] neg_lo:[0,1] neg_hi:[0,1]
	v_pk_add_f32 v[76:77], v[68:69], v[74:75]
	v_mov_b32_e32 v71, v68
	v_mov_b32_e32 v73, v77
	v_pk_add_f32 v[78:79], v[70:71], v[72:73] neg_lo:[0,1] neg_hi:[0,1]
	v_pk_add_f32 v[70:71], v[70:71], v[72:73]
	v_mov_b32_e32 v74, v75
	v_pk_add_f32 v[72:73], v[70:71], v[68:69] op_sel:[1,0] op_sel_hi:[0,1] neg_lo:[0,1] neg_hi:[0,1]
	v_pk_add_f32 v[82:83], v[76:77], v[72:73] op_sel_hi:[1,0] neg_lo:[0,1] neg_hi:[0,1]
	v_mov_b32_e32 v76, v77
	v_mov_b32_e32 v77, v71
	v_pk_mov_b32 v[72:73], v[68:69], v[72:73] op_sel:[1,0]
	v_mov_b32_e32 v75, v68
	v_pk_add_f32 v[72:73], v[76:77], v[72:73] neg_lo:[0,1] neg_hi:[0,1]
	v_mov_b32_e32 v82, v78
	v_pk_add_f32 v[68:69], v[74:75], v[72:73] neg_lo:[0,1] neg_hi:[0,1]
	v_mov_b32_e32 v79, v71
	v_pk_add_f32 v[72:73], v[82:83], v[68:69]
	s_nop 0
	v_pk_add_f32 v[74:75], v[72:73], v[72:73] op_sel:[0,1] op_sel_hi:[1,0]
	s_nop 0
	v_pk_add_f32 v[70:71], v[70:71], v[74:75] op_sel:[1,0] op_sel_hi:[0,1]
	v_mov_b32_e32 v73, v70
	v_pk_add_f32 v[76:77], v[72:73], v[78:79] neg_lo:[0,1] neg_hi:[0,1]
	v_mov_b32_e32 v69, v74
	v_sub_f32_e32 v71, v72, v76
	v_pk_add_f32 v[68:69], v[68:69], v[76:77] neg_lo:[0,1] neg_hi:[0,1]
	v_sub_f32_e32 v71, v78, v71
	v_add_f32_e32 v68, v68, v71
	v_add_f32_e32 v68, v68, v69
	v_add_f32_e32 v68, v70, v68
	v_cndmask_b32_e32 v68, v183, v68, vcc
	v_cmp_ngt_f32_e32 vcc, -1.0, v81
	s_nop 1
	v_cndmask_b32_e32 v68, v184, v68, vcc
	v_cmp_neq_f32_e32 vcc, -1.0, v81
	s_nop 1
	v_cndmask_b32_e32 v68, v185, v68, vcc
	v_cmp_lt_f32_e64 vcc, |v81|, s12
	s_nop 1
	v_cndmask_b32_e32 v68, v68, v81, vcc

; __device__ __forceinline__ float siluf_(float x) { return x * frcp_(1.0f + __expf(-x)); }
; __device__ __forceinline__ float softplusf_(float x) { return x > 20.f ? x : log1pf(__expf(x)); }
; __device__ __forceinline__ void ssd_sample_step(const bf16* proj, const float* conv_w, const float* conv_b, const float* dt_bias, const float* a_log, const float* d_skip, const float* ssm_norm, ...
;     ...
;         const float a = cbb + cw0 * r0 + cw1 * r1 + cw2 * r2 + cw3 * cur;
;         const float v = siluf_(a);
;         if (tid < 256) sx[tid] = v; else if (tid < 384) sB[tid - 256] = v; else sC[tid - 384] = v;
;         float* co = conv_out + (size_t)b * 3 * 4096; co[chx] = r1; co[4096 + chx] = r2; co[8192 + chx] = cur;
;         if (tid < 4) { const float dv = softplusf_(dtr + dtbv); sdt[tid] = dv; sdec[tid] = __expf(dv * (-__expf(alg))); } }
.LBB0_599:
	s_or_saveexec_b64 s[6:7], s[6:7]
	v_lshl_add_u32 v10, v8, 2, 0
	s_xor_b64 exec, exec, s[6:7]
	ds_write_b32 v10, v75 offset:2048
	s_or_b64 exec, exec, s[6:7]
	s_add_u32 s6, s62, s12
	s_addc_u32 s7, s63, s13
	v_lshl_add_u64 v[68:69], v[68:69], 2, s[6:7]
	v_add_co_u32_e32 v76, vcc, 0x4000, v68
	global_store_dword v[68:69], v70, off nt
	s_nop 0
	v_addc_co_u32_e32 v77, vcc, 0, v69, vcc
	v_add_co_u32_e32 v68, vcc, 0x8000, v68
	global_store_dword v[76:77], v71, off nt
	s_nop 0
	v_addc_co_u32_e32 v69, vcc, 0, v69, vcc
	global_store_dword v[68:69], v74, off nt
	s_and_saveexec_b64 s[6:7], s[8:9]
	s_cbranch_execz .LBB0_605
	v_add_f32_e32 v68, v73, v72
	v_cmp_nlt_f32_e32 vcc, s54, v68
	s_and_saveexec_b64 s[8:9], vcc
	s_cbranch_execz .LBB0_604
	v_mul_f32_e32 v68, 0x3fb8aa3b, v68
	v_exp_f32_e32 v81, v68
	s_mov_b32 s12, 0x3f2aaaab
	v_add_f32_e32 v70, 1.0, v81
	v_frexp_mant_f32_e32 v72, v70
	v_cvt_f64_f32_e32 v[68:69], v70
	v_frexp_exp_i32_f64_e32 v68, v[68:69]
	v_cmp_gt_f32_e32 vcc, s12, v72
	v_add_f32_e32 v71, -1.0, v70
	v_sub_f32_e32 v73, v71, v70
	v_subbrev_co_u32_e32 v76, vcc, 0, v68, vcc
	v_sub_u32_e32 v68, 0, v76
	v_sub_f32_e32 v71, v81, v71
	v_add_f32_e32 v73, 1.0, v73
	v_ldexp_f32 v69, v70, v68
	v_add_f32_e32 v71, v71, v73
	v_add_f32_e32 v70, -1.0, v69
	v_add_f32_e32 v72, 1.0, v69
	v_ldexp_f32 v68, v71, v68
	v_add_f32_e32 v71, 1.0, v70
	v_add_f32_e32 v73, -1.0, v72
	v_sub_f32_e32 v71, v69, v71
	v_sub_f32_e32 v69, v69, v73
	v_add_f32_e32 v71, v68, v71
	v_add_f32_e32 v68, v68, v69
	v_add_f32_e32 v77, v72, v68
	v_rcp_f32_e32 v79, v77
	v_sub_f32_e32 v69, v77, v72
	v_sub_f32_e32 v78, v68, v69
	v_add_f32_e32 v69, v70, v71
	v_mul_f32_e32 v83, v69, v79
	v_sub_f32_e32 v68, v69, v70
	v_mul_f32_e32 v70, v77, v83
	v_fma_f32 v72, v83, v77, -v70
	v_fmac_f32_e32 v72, v83, v78
	v_sub_f32_e32 v82, v71, v68
	v_add_f32_e32 v68, v70, v72
	v_sub_f32_e32 v71, v69, v68
	v_pk_add_f32 v[74:75], v[68:69], v[70:71] neg_lo:[0,1] neg_hi:[0,1]
	v_mov_b32_e32 v73, v68
	v_pk_add_f32 v[68:69], v[74:75], v[72:73] neg_lo:[0,1] neg_hi:[0,1]
	s_mov_b32 s12, 0x3f317218
	v_add_f32_e32 v69, v82, v69
	v_add_f32_e32 v68, v68, v69
	v_add_f32_e32 v69, v71, v68
	v_mul_f32_e32 v82, v79, v69
	v_mul_f32_e32 v70, v77, v82
	v_fma_f32 v72, v82, v77, -v70
	v_fmac_f32_e32 v72, v82, v78
	v_sub_f32_e32 v71, v71, v69
	v_add_f32_e32 v77, v68, v71
	v_add_f32_e32 v68, v70, v72
	v_sub_f32_e32 v71, v69, v68
	v_pk_add_f32 v[74:75], v[68:69], v[70:71] neg_lo:[0,1] neg_hi:[0,1]
	v_mov_b32_e32 v73, v68
	v_pk_add_f32 v[68:69], v[74:75], v[72:73] neg_lo:[0,1] neg_hi:[0,1]
	v_cmp_neq_f32_e32 vcc, s81, v81
	v_add_f32_e32 v69, v77, v69
	v_add_f32_e32 v68, v68, v69
	v_add_f32_e32 v69, v83, v82
	v_add_f32_e32 v68, v71, v68
	v_sub_f32_e32 v70, v69, v83
	v_mul_f32_e32 v68, v79, v68
	v_sub_f32_e32 v70, v82, v70
	v_add_f32_e32 v70, v70, v68
	v_add_f32_e32 v72, v69, v70
	v_mul_f32_e32 v73, v72, v72
	v_fmamk_f32 v68, v73, 0x3e9b6dac, v178
	v_fmaak_f32 v149, v73, v68, 0x3f2aaada
	v_cvt_f32_i32_e32 v68, v76
	v_sub_f32_e32 v69, v72, v69
	v_sub_f32_e32 v69, v70, v69
	v_ldexp_f32 v74, v69, 1
	v_mul_f32_e32 v69, v72, v73
	v_ldexp_f32 v71, v72, 1
	v_pk_mul_f32 v[72:73], v[68:69], v[148:149]
	s_nop 0
	v_fma_f32 v70, v68, s12, -v72
	v_fmac_f32_e32 v70, 0xb102e308, v68
	v_pk_add_f32 v[68:69], v[72:73], v[70:71]
	s_mov_b32 s12, 0x33800000
	v_sub_f32_e32 v71, v69, v71
	v_sub_f32_e32 v71, v73, v71
	v_add_f32_e32 v75, v74, v71
	v_mov_b32_e32 v74, v72
	v_pk_add_f32 v[72:73], v[68:69], v[72:73] neg_lo:[0,1] neg_hi:[0,1]
	v_pk_add_f32 v[76:77], v[68:69], v[74:75]
	v_mov_b32_e32 v71, v68
	v_mov_b32_e32 v73, v77
	v_pk_add_f32 v[78:79], v[70:71], v[72:73] neg_lo:[0,1] neg_hi:[0,1]
	v_pk_add_f32 v[70:71], v[70:71], v[72:73]
	v_mov_b32_e32 v74, v75
	v_pk_add_f32 v[72:73], v[70:71], v[68:69] op_sel:[1,0] op_sel_hi:[0,1] neg_lo:[0,1] neg_hi:[0,1]
	v_pk_add_f32 v[82:83], v[76:77], v[72:73] op_sel_hi:[1,0] neg_lo:[0,1] neg_hi:[0,1]
	v_mov_b32_e32 v76, v77
	v_mov_b32_e32 v77, v71
	v_pk_mov_b32 v[72:73], v[68:69], v[72:73] op_sel:[1,0]
	v_mov_b32_e32 v75, v68
	v_pk_add_f32 v[72:73], v[76:77], v[72:73] neg_lo:[0,1] neg_hi:[0,1]
	v_mov_b32_e32 v82, v78
	v_pk_add_f32 v[68:69], v[74:75], v[72:73] neg_lo:[0,1] neg_hi:[0,1]
	v_mov_b32_e32 v79, v71
	v_pk_add_f32 v[72:73], v[82:83], v[68:69]
	s_nop 0
	v_pk_add_f32 v[74:75], v[72:73], v[72:73] op_sel:[0,1] op_sel_hi:[1,0]
	s_nop 0
	v_pk_add_f32 v[70:71], v[70:71], v[74:75] op_sel:[1,0] op_sel_hi:[0,1]
	v_mov_b32_e32 v73, v70
	v_pk_add_f32 v[76:77], v[72:73], v[78:79] neg_lo:[0,1] neg_hi:[0,1]
	v_mov_b32_e32 v69, v74
	v_sub_f32_e32 v71, v72, v76
	v_pk_add_f32 v[68:69], v[68:69], v[76:77] neg_lo:[0,1] neg_hi:[0,1]
	v_sub_f32_e32 v71, v78, v71
	v_add_f32_e32 v68, v68, v71
	v_add_f32_e32 v68, v68, v69
	v_add_f32_e32 v68, v70, v68
	v_cndmask_b32_e32 v68, v183, v68, vcc
	v_cmp_ngt_f32_e32 vcc, -1.0, v81
	s_nop 1
	v_cndmask_b32_e32 v68, v184, v68, vcc
	v_cmp_neq_f32_e32 vcc, -1.0, v81
	s_nop 1
	v_cndmask_b32_e32 v68, v185, v68, vcc
	v_cmp_lt_f32_e64 vcc, |v81|, s12
	s_nop 1
	v_cndmask_b32_e32 v68, v68, v81, vcc
